# v16 + pass2 prepare/norm: 48 scalar f32 multiplies as 24 v_pk_mul_f32 (bit-identical)
# baseline (speedup 1.0000x reference)
.LBB0_1330:
	s_add_i32 s26, s26, 1
	s_mov_b64 s[20:21], 0x10000
	v_lshl_add_u32 v160, v95, 5, s27
	ds_read_b128 v[148:151], v160 offset:57344
	ds_read_b128 v[152:155], v160 offset:57360
	ds_read_b128 v[156:159], v160 offset:57856
	ds_read_b128 v[162:165], v160 offset:57872
	v_add3_u32 v125, s27, v109, v222
	ds_read_b64 v[166:167], v125 offset:48128
	ds_read_b64 v[168:169], v125 offset:52480
	s_waitcnt vmcnt(4)
	s_waitcnt lgkmcnt(4)
	v_add_f32_e32 v170, v148, v149
	v_add_f32_e32 v171, v150, v151
	v_add_f32_e32 v172, v152, v153
	v_add_f32_e32 v170, v170, v171
	v_add_f32_e32 v173, v154, v155
	v_add_f32_e32 v172, v172, v173
	v_add_f32_e32 v170, v170, v172
	v_fmamk_f32 v170, v170, 0x3c000000, v218
	v_rsq_f32_e32 v170, v170
	s_waitcnt lgkmcnt(2)
	v_add_f32_e32 v174, v156, v157
	v_add_f32_e32 v175, v158, v159
	v_add_f32_e32 v176, v162, v163
	v_add_f32_e32 v174, v174, v175
	v_add_f32_e32 v177, v164, v165
	v_add_f32_e32 v176, v176, v177
	v_add_f32_e32 v174, v174, v176
	v_fmamk_f32 v174, v174, 0x3c000000, v218
	v_rsq_f32_e32 v174, v174
	s_waitcnt lgkmcnt(0)
	v_lshlrev_b32_e32 v178, 16, v166
	v_and_b32_e32 v179, 0xffff0000, v166
	v_lshlrev_b32_e32 v200, 16, v167
	v_and_b32_e32 v201, 0xffff0000, v167
	v_lshlrev_b32_e32 v202, 16, v168
	v_and_b32_e32 v203, 0xffff0000, v168
	v_lshlrev_b32_e32 v204, 16, v169
	v_and_b32_e32 v205, 0xffff0000, v169
	v_pk_mul_f32 v[206:207], v[62:63], v[170:171] op_sel_hi:[1,0]
	v_pk_mul_f32 v[208:209], v[64:65], v[170:171] op_sel_hi:[1,0]
	v_pk_mul_f32 v[210:211], v[58:59], v[174:175] op_sel_hi:[1,0]
	v_pk_mul_f32 v[212:213], v[60:61], v[174:175] op_sel_hi:[1,0]
	v_pk_mul_f32 v[206:207], v[224:225], v[206:207]
	v_pk_mul_f32 v[208:209], v[226:227], v[208:209]
	v_pk_mul_f32 v[210:211], v[224:225], v[210:211]
	v_pk_mul_f32 v[212:213], v[226:227], v[212:213]
	v_pk_mul_f32 v[206:207], v[206:207], v[178:179]
	v_pk_mul_f32 v[208:209], v[208:209], v[200:201]
	v_pk_mul_f32 v[210:211], v[210:211], v[202:203]
	v_pk_mul_f32 v[212:213], v[212:213], v[204:205]
	v_cvt_pk_bf16_f32 v148, v206, v207
	v_cvt_pk_bf16_f32 v149, v208, v209
	v_cvt_pk_bf16_f32 v150, v210, v211
	v_cvt_pk_bf16_f32 v151, v212, v213
	ds_write_b64 v125, v[148:149] offset:8704
	ds_write_b64 v125, v[150:151] offset:13056
	s_cmp_lg_u32 s26, 8
	s_waitcnt lgkmcnt(0)
	s_barrier
	v_add3_u32 v58, s27, v93, v80
	ds_read_b128 v[58:61], v58 offset:8704
	s_waitcnt lgkmcnt(0)
	global_store_dwordx4 v[88:89], v[58:61], off
	v_lshl_add_u64 v[88:89], v[88:89], 0, s[20:21]
	s_mov_b64 s[20:21], 0x2c000
	v_lshl_add_u64 v[90:91], v[90:91], 0, s[20:21]
	s_cbranch_scc0 .LBB0_1325

.LBB0_1334:
	s_mul_i32 s22, s22, 0xe400
	s_add_i32 s27, s22, 0
	v_add3_u32 v147, s27, v104, v109
	s_add_i32 s29, s27, s19
	ds_read_b64 v[148:149], v147
	ds_read_b64 v[150:151], v147 offset:32
	ds_read_b64 v[152:153], v147 offset:4352
	ds_read_b64 v[154:155], v147 offset:4384
	ds_read_b64 v[196:197], v147 offset:8704
	ds_read_b64 v[198:199], v147 offset:8736
	ds_read_b64 v[200:201], v147 offset:13056
	ds_read_b64 v[202:203], v147 offset:13088
	v_cvt_pk_bf16_f32 v126, v26, v27
	v_cvt_pk_bf16_f32 v127, v28, v29
	v_cvt_pk_bf16_f32 v128, v30, v31
	v_cvt_pk_bf16_f32 v129, v32, v33
	ds_read_b64 v[156:157], v147 offset:64
	ds_read_b64 v[158:159], v147 offset:96
	ds_read_b64 v[160:161], v147 offset:4416
	ds_read_b64 v[162:163], v147 offset:4448
	ds_read_b64 v[204:205], v147 offset:8768
	ds_read_b64 v[206:207], v147 offset:8800
	ds_read_b64 v[208:209], v147 offset:13120
	ds_read_b64 v[210:211], v147 offset:13152
	v_cvt_pk_bf16_f32 v130, v34, v35
	v_cvt_pk_bf16_f32 v131, v36, v37
	v_cvt_pk_bf16_f32 v132, v38, v39
	v_cvt_pk_bf16_f32 v133, v40, v41
	s_waitcnt lgkmcnt(8)
	v_mfma_f32_16x16x32_bf16 v[62:65], v[126:129], v[148:151], 0
	v_mfma_f32_16x16x32_bf16 v[58:61], v[126:129], v[152:155], 0
	v_mfma_f32_16x16x32_bf16 v[164:167], v[196:199], v[148:151], 0
	v_mfma_f32_16x16x32_bf16 v[168:171], v[196:199], v[152:155], 0
	v_mfma_f32_16x16x32_bf16 v[172:175], v[200:203], v[152:155], 0
	ds_read_b64 v[148:149], v147 offset:128
	ds_read_b64 v[150:151], v147 offset:160
	ds_read_b64 v[152:153], v147 offset:4480
	ds_read_b64 v[154:155], v147 offset:4512
	ds_read_b64 v[196:197], v147 offset:8832
	ds_read_b64 v[198:199], v147 offset:8864
	ds_read_b64 v[200:201], v147 offset:13184
	ds_read_b64 v[202:203], v147 offset:13216
	v_cvt_pk_bf16_f32 v134, v42, v43
	v_cvt_pk_bf16_f32 v135, v44, v45
	v_cvt_pk_bf16_f32 v136, v46, v47
	v_cvt_pk_bf16_f32 v137, v48, v49
	s_waitcnt lgkmcnt(8)
	v_mfma_f32_16x16x32_bf16 v[62:65], v[130:133], v[156:159], v[62:65]
	v_mfma_f32_16x16x32_bf16 v[58:61], v[130:133], v[160:163], v[58:61]
	v_mfma_f32_16x16x32_bf16 v[164:167], v[204:207], v[156:159], v[164:167]
	v_mfma_f32_16x16x32_bf16 v[168:171], v[204:207], v[160:163], v[168:171]
	v_mfma_f32_16x16x32_bf16 v[172:175], v[208:211], v[160:163], v[172:175]
	ds_read_b64 v[156:157], v147 offset:192
	ds_read_b64 v[158:159], v147 offset:224
	ds_read_b64 v[160:161], v147 offset:4544
	ds_read_b64 v[162:163], v147 offset:4576
	ds_read_b64 v[204:205], v147 offset:8896
	ds_read_b64 v[206:207], v147 offset:8928
	ds_read_b64 v[208:209], v147 offset:13248
	ds_read_b64 v[210:211], v147 offset:13280
	v_cvt_pk_bf16_f32 v138, v50, v51
	v_cvt_pk_bf16_f32 v139, v52, v53
	v_cvt_pk_bf16_f32 v140, v54, v55
	v_cvt_pk_bf16_f32 v141, v56, v57
	s_waitcnt lgkmcnt(8)
	v_mfma_f32_16x16x32_bf16 v[62:65], v[134:137], v[148:151], v[62:65]
	v_mfma_f32_16x16x32_bf16 v[58:61], v[134:137], v[152:155], v[58:61]
	v_mfma_f32_16x16x32_bf16 v[164:167], v[196:199], v[148:151], v[164:167]
	v_mfma_f32_16x16x32_bf16 v[168:171], v[196:199], v[152:155], v[168:171]
	v_mfma_f32_16x16x32_bf16 v[172:175], v[200:203], v[152:155], v[172:175]
	v_add_u32_e32 v176, s27, v106
	v_add_u32_e32 v68, v176, v123
	ds_read_b64_tr_b16 v[66:67], v68 offset:37888
	ds_read_b64_tr_b16 v[68:69], v68 offset:43008
	s_waitcnt lgkmcnt(2)
	v_mfma_f32_16x16x32_bf16 v[62:65], v[138:141], v[156:159], v[62:65]
	v_mfma_f32_16x16x32_bf16 v[58:61], v[138:141], v[160:163], v[58:61]
	v_mfma_f32_16x16x32_bf16 v[164:167], v[204:207], v[156:159], v[164:167]
	v_mfma_f32_16x16x32_bf16 v[168:171], v[204:207], v[160:163], v[168:171]
	v_mfma_f32_16x16x32_bf16 v[172:175], v[208:211], v[160:163], v[172:175]
	v_add_u32_e32 v125, s27, v105
	v_add_u32_e32 v134, v176, v110
	v_mov_b32_e32 v177, s55
	v_mov_b32_e32 v72, v16
	v_mov_b32_e32 v73, v16
	s_nop 0
	v_cndmask_b32_e64 v165, 0, v165, s[6:7]
	v_cndmask_b32_e64 v166, v166, 0, s[8:9]
	v_cndmask_b32_e64 v167, v167, 0, s[10:11]
	v_cndmask_b32_e64 v164, v164, v177, s[4:5]
	v_cvt_pk_bf16_f32 v70, v164, v165
	v_cvt_pk_bf16_f32 v71, v166, v167
	v_cndmask_b32_e64 v172, v172, v177, s[4:5]
	v_cndmask_b32_e64 v173, v173, 0, s[12:13]
	v_cndmask_b32_e64 v174, v174, 0, s[14:15]
	v_cndmask_b32_e64 v175, v175, 0, s[16:17]
	s_waitcnt lgkmcnt(0)
	v_mfma_f32_16x16x32_bf16 v[62:65], v[66:69], v[70:73], v[62:65]
	v_cvt_pk_bf16_f32 v70, v168, v169
	v_cvt_pk_bf16_f32 v71, v170, v171
	v_cvt_pk_bf16_f32 v72, v172, v173
	v_cvt_pk_bf16_f32 v73, v174, v175
	s_nop 1
	v_mfma_f32_16x16x32_bf16 v[58:61], v[66:69], v[70:73], v[58:61]
	ds_read_b128 v[160:163], v125 offset:56832
	ds_read_b64_tr_b16 v[148:149], v134 offset:27648
	ds_read_b64_tr_b16 v[150:151], v134 offset:32768
	ds_read_b128 v[164:167], v125 offset:56896
	ds_read_b64_tr_b16 v[152:153], v134 offset:27680
	ds_read_b64_tr_b16 v[154:155], v134 offset:32800
	s_waitcnt lgkmcnt(3)
	v_pk_mul_f32 v[26:27], v[26:27], v[160:161]
	v_pk_mul_f32 v[28:29], v[28:29], v[162:163]
	ds_read_b128 v[168:171], v125 offset:56960
	ds_read_b64_tr_b16 v[156:157], v134 offset:27712
	ds_read_b64_tr_b16 v[158:159], v134 offset:32832
	v_mfma_f32_16x16x32_bf16 v[26:29], v[148:151], v[66:69], v[26:29]
	s_waitcnt lgkmcnt(3)
	v_pk_mul_f32 v[30:31], v[30:31], v[164:165]
	v_pk_mul_f32 v[32:33], v[32:33], v[166:167]
	ds_read_b128 v[160:163], v125 offset:57024
	ds_read_b64_tr_b16 v[148:149], v134 offset:27744
	ds_read_b64_tr_b16 v[150:151], v134 offset:32864
	v_mfma_f32_16x16x32_bf16 v[30:33], v[152:155], v[66:69], v[30:33]
	s_waitcnt lgkmcnt(3)
	v_pk_mul_f32 v[34:35], v[34:35], v[168:169]
	v_pk_mul_f32 v[36:37], v[36:37], v[170:171]
	ds_read_b128 v[164:167], v125 offset:57088
	ds_read_b64_tr_b16 v[152:153], v134 offset:27776
	ds_read_b64_tr_b16 v[154:155], v134 offset:32896
	v_mfma_f32_16x16x32_bf16 v[34:37], v[156:159], v[66:69], v[34:37]
	s_waitcnt lgkmcnt(3)
	v_pk_mul_f32 v[38:39], v[38:39], v[160:161]
	v_pk_mul_f32 v[40:41], v[40:41], v[162:163]
	ds_read_b128 v[168:171], v125 offset:57152
	ds_read_b64_tr_b16 v[156:157], v134 offset:27808
	ds_read_b64_tr_b16 v[158:159], v134 offset:32928
	v_mfma_f32_16x16x32_bf16 v[38:41], v[148:151], v[66:69], v[38:41]
	s_waitcnt lgkmcnt(3)
	v_pk_mul_f32 v[42:43], v[42:43], v[164:165]
	v_pk_mul_f32 v[44:45], v[44:45], v[166:167]
	ds_read_b128 v[160:163], v125 offset:57216
	ds_read_b64_tr_b16 v[148:149], v134 offset:27840
	ds_read_b64_tr_b16 v[150:151], v134 offset:32960
	v_mfma_f32_16x16x32_bf16 v[42:45], v[152:155], v[66:69], v[42:45]
	s_waitcnt lgkmcnt(3)
	v_pk_mul_f32 v[46:47], v[46:47], v[168:169]
	v_pk_mul_f32 v[48:49], v[48:49], v[170:171]
	ds_read_b128 v[164:167], v125 offset:57280
	ds_read_b64_tr_b16 v[152:153], v134 offset:27872
	ds_read_b64_tr_b16 v[154:155], v134 offset:32992
	v_mfma_f32_16x16x32_bf16 v[46:49], v[156:159], v[66:69], v[46:49]
	s_waitcnt lgkmcnt(3)
	v_pk_mul_f32 v[50:51], v[50:51], v[160:161]
	v_pk_mul_f32 v[52:53], v[52:53], v[162:163]
	s_nop 1
	v_mfma_f32_16x16x32_bf16 v[50:53], v[148:151], v[66:69], v[50:53]
	s_waitcnt lgkmcnt(0)
	v_pk_mul_f32 v[54:55], v[54:55], v[164:165]
	v_pk_mul_f32 v[56:57], v[56:57], v[166:167]
	s_nop 1
	v_mfma_f32_16x16x32_bf16 v[54:57], v[152:155], v[66:69], v[54:57]
	v_mul_f32_e32 v148, v62, v62
	v_mul_f32_e32 v149, v58, v58
	v_fmac_f32_e32 v148, v63, v63
	v_fmac_f32_e32 v149, v59, v59
	v_fmac_f32_e32 v148, v64, v64
	v_fmac_f32_e32 v149, v60, v60
	v_fmac_f32_e32 v148, v65, v65
	v_fmac_f32_e32 v149, v61, v61
	v_lshl_add_u32 v156, v77, 5, s29
	s_nop 0
	v_permlane16_swap_b32_e32 v148, v149
	v_add_f32_e32 v148, v148, v149
	v_mov_b32_e32 v149, v148
	s_nop 1
	v_permlane32_swap_b32_e32 v148, v149
	v_add_f32_e32 v148, v148, v149
	s_mov_b64 s[22:23], exec
	s_mov_b32 exec_hi, 0
	ds_write_b32 v156, v148 offset:57344
	s_mov_b64 exec, s[22:23]
	s_waitcnt lgkmcnt(0)
	s_barrier
	s_andn2_b64 vcc, exec, s[20:21]
	s_cbranch_vccnz .LBB0_1330
	v_add3_u32 v68, s28, v96, v120
	ds_read_b64_tr_b16 v[66:67], v68 offset:17408
	ds_read_b64_tr_b16 v[68:69], v68 offset:18688
	v_add_u32_e32 v138, s28, v236
	v_add3_u32 v139, s28, v109, v222
	ds_read_b64 v[180:181], v138 offset:17408
	ds_read_b64 v[182:183], v138 offset:22528
	ds_read_b64 v[184:185], v139
	ds_read_b64 v[186:187], v139 offset:4352
	s_waitcnt lgkmcnt(4)
	v_mfma_f32_16x16x32_bf16 v[70:73], v[66:69], v[4:7], 0
	v_mfma_f32_16x16x32_bf16 v[66:69], v[66:69], v[0:3], 0
	s_mov_b32 s23, 0x42e60000
	s_waitcnt lgkmcnt(0)
	v_lshlrev_b32_e32 v188, 16, v180
	v_and_b32_e32 v189, 0xffff0000, v180
	v_lshlrev_b32_e32 v190, 16, v181
	v_and_b32_e32 v191, 0xffff0000, v181
	v_lshlrev_b32_e32 v192, 16, v182
	v_and_b32_e32 v193, 0xffff0000, v182
	v_lshlrev_b32_e32 v194, 16, v183
	v_and_b32_e32 v195, 0xffff0000, v183
	v_lshlrev_b32_e32 v196, 16, v184
	v_and_b32_e32 v197, 0xffff0000, v184
	v_lshlrev_b32_e32 v198, 16, v185
	v_and_b32_e32 v199, 0xffff0000, v185
	v_lshlrev_b32_e32 v200, 16, v186
	v_and_b32_e32 v201, 0xffff0000, v186
	v_lshlrev_b32_e32 v202, 16, v187
	v_and_b32_e32 v203, 0xffff0000, v187
	v_exp_f32_e32 v188, v188
	v_exp_f32_e32 v189, v189
	v_exp_f32_e32 v190, v190
	v_exp_f32_e32 v191, v191
	v_exp_f32_e32 v192, v192
	v_exp_f32_e32 v193, v193
	v_exp_f32_e32 v194, v194
	v_exp_f32_e32 v195, v195
	v_sub_f32_e32 v188, 1.0, v188
	v_sub_f32_e32 v189, 1.0, v189
	v_sub_f32_e32 v190, 1.0, v190
	v_sub_f32_e32 v191, 1.0, v191
	v_sub_f32_e32 v192, 1.0, v192
	v_sub_f32_e32 v193, 1.0, v193
	v_sub_f32_e32 v194, 1.0, v194
	v_sub_f32_e32 v195, 1.0, v195
	v_exp_f32_e32 v204, v70
	v_exp_f32_e32 v205, v71
	v_exp_f32_e32 v206, v72
	v_exp_f32_e32 v207, v73
	v_exp_f32_e32 v208, v66
	v_exp_f32_e32 v209, v67
	v_exp_f32_e32 v210, v68
	v_exp_f32_e32 v211, v69
	v_sub_f32_dpp v126, v66, v70 row_newbcast:15 row_mask:0xf bank_mask:0xf
	v_sub_f32_dpp v127, v67, v71 row_newbcast:15 row_mask:0xf bank_mask:0xf
	v_sub_f32_dpp v128, v68, v72 row_newbcast:15 row_mask:0xf bank_mask:0xf
	v_sub_f32_dpp v129, v69, v73 row_newbcast:15 row_mask:0xf bank_mask:0xf
	v_sub_f32_dpp v130, v66, v66 row_newbcast:15 row_mask:0xf bank_mask:0xf
	v_sub_f32_dpp v131, v67, v67 row_newbcast:15 row_mask:0xf bank_mask:0xf
	v_sub_f32_dpp v132, v68, v68 row_newbcast:15 row_mask:0xf bank_mask:0xf
	v_sub_f32_dpp v133, v69, v69 row_newbcast:15 row_mask:0xf bank_mask:0xf
	v_pk_mul_f32 v[196:197], v[196:197], v[204:205]
	v_pk_mul_f32 v[198:199], v[198:199], v[206:207]
	v_pk_mul_f32 v[200:201], v[200:201], v[208:209]
	v_pk_mul_f32 v[202:203], v[202:203], v[210:211]
	v_min_f32_e64 v204, -v70, s23
	v_min_f32_e64 v205, -v71, s23
	v_min_f32_e64 v206, -v72, s23
	v_min_f32_e64 v207, -v73, s23
	v_min_f32_e64 v208, -v66, s23
	v_min_f32_e64 v209, -v67, s23
	v_min_f32_e64 v210, -v68, s23
	v_min_f32_e64 v211, -v69, s23
	v_exp_f32_e32 v126, v126
	v_exp_f32_e32 v127, v127
	v_exp_f32_e32 v128, v128
	v_exp_f32_e32 v129, v129
	v_exp_f32_e32 v130, v130
	v_exp_f32_e32 v131, v131
	v_exp_f32_e32 v132, v132
	v_exp_f32_e32 v133, v133
	v_exp_f32_e32 v204, v204
	v_exp_f32_e32 v205, v205
	v_exp_f32_e32 v206, v206
	v_exp_f32_e32 v207, v207
	v_exp_f32_e32 v208, v208
	v_exp_f32_e32 v209, v209
	v_exp_f32_e32 v210, v210
	v_exp_f32_e32 v211, v211
	v_exp_f32_e32 v212, v66
	v_exp_f32_e32 v213, v67
	v_exp_f32_e32 v214, v68
	v_exp_f32_e32 v215, v69
	v_pk_mul_f32 v[126:127], v[126:127], v[188:189]
	v_pk_mul_f32 v[128:129], v[128:129], v[190:191]
	v_pk_mul_f32 v[130:131], v[130:131], v[192:193]
	v_pk_mul_f32 v[132:133], v[132:133], v[194:195]
	v_pk_mul_f32 v[204:205], v[204:205], v[188:189]
	v_pk_mul_f32 v[206:207], v[206:207], v[190:191]
	v_pk_mul_f32 v[208:209], v[208:209], v[192:193]
	v_pk_mul_f32 v[210:211], v[210:211], v[194:195]
	v_lshl_add_u32 v216, v222, 1, s28
	v_cvt_pk_bf16_f32 v180, v196, v197
	v_cvt_pk_bf16_f32 v181, v198, v199
	v_cvt_pk_bf16_f32 v182, v200, v201
	v_cvt_pk_bf16_f32 v183, v202, v203
	v_cvt_pk_bf16_f32 v184, v204, v205
	v_cvt_pk_bf16_f32 v185, v206, v207
	v_cvt_pk_bf16_f32 v186, v208, v209
	v_cvt_pk_bf16_f32 v187, v210, v211
	v_cvt_pk_bf16_f32 v134, v126, v127
	v_cvt_pk_bf16_f32 v135, v128, v129
	v_cvt_pk_bf16_f32 v136, v130, v131
	v_cvt_pk_bf16_f32 v137, v132, v133
	ds_write_b64 v139, v[180:181]
	ds_write_b64 v139, v[182:183] offset:4352
	ds_write_b64 v139, v[184:185] offset:8704
	ds_write_b64 v139, v[186:187] offset:13056
	ds_write_b64 v138, v[134:135] offset:27648
	ds_write_b64 v138, v[136:137] offset:32768
	s_and_saveexec_b64 s[20:21], s[2:3]
	ds_write_b128 v216, v[212:215] offset:56832
	s_branch .LBB0_1329
